# SEAM4 4-workgroup same-XCD arrival counter, guard = per-residue XCC_ID consistency (max/min words), else grid barrier
# speedup vs baseline: 1.0081x; 1.0075x over previous
.LBB0_30:
	s_cmp_gt_i32 s91, 1
	s_cselect_b64 s[4:5], -1, 0
	s_and_b64 s[6:7], s[6:7], s[4:5]
	s_andn2_b64 vcc, exec, s[6:7]
	s_cbranch_vccnz .LBB0_85
	s_waitcnt vmcnt(0) lgkmcnt(0)
	s_barrier
	v_readlane_b32 s6, v255, 2
	v_readlane_b32 s7, v255, 3
	s_mov_b64 s[8:9], exec
	s_and_b64 exec, exec, s[6:7]
	s_cbranch_execz .Lp0_arrived
	v_mov_b32_e32 v0, 0
	v_mov_b32_e32 v1, 1
	global_atomic_add v0, v1, s[88:89] offset:2048
	s_getreg_b32 s98, hwreg(HW_REG_XCC_ID, 0, 4)
	s_and_b32 s98, s98, 15
	s_and_b32 s99, s2, 7
	s_lshl_b32 s99, s99, 3
	s_add_i32 s99, s99, 0xe000
	v_mov_b32_e32 v0, s99
	s_add_i32 s99, s98, 1
	s_sub_i32 s98, 16, s98
	s_cmpk_eq_u32 s33, 0x100
	s_cselect_b32 s99, s99, 100
	v_mov_b32_e32 v2, s99
	v_mov_b32_e32 v3, s98
	global_atomic_umax v0, v2, s[88:89]
	global_atomic_umax v0, v3, s[88:89] offset:4

.LBB0_511:
	s_cmp_gt_i32 s91, 5
	s_cselect_b64 s[4:5], -1, 0
	s_and_b64 s[0:1], s[0:1], s[4:5]
	s_andn2_b64 vcc, exec, s[0:1]
	s_cbranch_vccnz .LBB0_565
	s_waitcnt vmcnt(0)
	s_waitcnt vmcnt(0) lgkmcnt(0)
	s_barrier
	s_and_saveexec_b64 s[0:1], s[84:85]
	s_cbranch_execz .LBB0_564
	s_and_b32 s98, s2, 7
	s_lshl_b32 s99, s98, 3
	s_add_i32 s99, s99, 0xe000
	v_mov_b32_e32 v0, s99
	global_load_dwordx2 v[4:5], v0, s[88:89] sc1
	s_lshl_b32 s98, s98, 3
	s_bfe_u32 s99, s2, 0x30003
	s_add_i32 s98, s98, s99
	s_lshl_b32 s98, s98, 6
	s_add_i32 s98, s98, 0xd000
	v_mov_b32_e32 v2, s98
	v_mov_b32_e32 v3, 1
	s_waitcnt vmcnt(0)
	v_add_u32_e32 v1, v4, v5
	v_cmp_ne_u32_e32 vcc, 17, v1
	s_cbranch_vccnz .Lg4_orig
	global_atomic_add v2, v3, s[88:89]
